# u1 publish: release L2 writeback dropped (payload stores are sc1 write-through and every wave drains vmcnt before counting, per the documented hand-off recipe)
# speedup vs baseline: 1.0087x; 1.0087x over previous
.LBB0_798:
	s_or_b64 exec, exec, s[28:29]
	v_readfirstlane_b32 s0, v0
	s_cmp_lg_u32 s0, 7
	s_mov_b32 s57, s24
	s_cbranch_scc1 .LBB0_805
	s_and_saveexec_b64 s[0:1], vcc
	v_mov_b32_e32 v0, s27
	ds_write_b32 v0, v65
	s_or_b64 exec, exec, s[0:1]
	s_waitcnt vmcnt(0) lgkmcnt(0)
	s_waitcnt vmcnt(0)
	s_and_saveexec_b64 s[0:1], vcc
	s_cbranch_execz .LBB0_804
	s_mov_b64 s[28:29], exec
	v_mbcnt_lo_u32_b32 v0, s28, 0
	v_mbcnt_hi_u32_b32 v0, s29, v0
	v_cmp_eq_u32_e32 vcc, 0, v0
	s_and_b64 s[4:5], exec, vcc
	s_mov_b64 exec, s[4:5]
	s_cbranch_execz .LBB0_804
	s_bcnt1_i32_b64 s4, s[28:29]
	s_lshl_b32 s4, s4, 3
	v_mov_b32_e32 v0, s4
	global_atomic_add v65, v0, s[2:3]
